# P3 pass-1 epilogue: 31 gate (u8x4) loads hoisted to the top of the epilogue into v188-219, vmcnt waits recounted
# speedup vs baseline: 1.0130x; 1.0053x over previous
; DI unsigned pk2(float a, float b) { f32x2 v = {a, b}; return __builtin_bit_cast(unsigned, __builtin_convertvector(v, bfv2)); }
; DI float bflo(unsigned u) { return __uint_as_float(u << 16); }
; DI float bfhi(unsigned u) { return __uint_as_float(u & 0xffff0000u); }
;     DI void operator()(const pg8::f32x4 (&acc)[2][2][4][2], const pg8::Unit& u, int wr, int wc, int fr, int fq) const {
;         const unsigned char* sg = ws + (PASS == 0 ? OFF_SGB : OFF_SGA);
;         bf16_t* merged = (bf16_t*)(ws + OFF_AK);
; #pragma unroll
;         for (int ai = 0; ai < 2; ++ai)
; #pragma unroll
;             for (int m = 0; m < 4; ++m) {
;                 const size_t tok = (size_t)u.pm * 256 + ai * 128 + wr * 64 + m * 16 + fr;
; #pragma unroll
;                 for (int bj = 0; bj < 2; ++bj)
; #pragma unroll
;                     for (int n = 0; n < 2; ++n) {
;                         const size_t off = tok * 1024 + u.pn * 256 + bj * 128 + wc * 32 + n * 16 + 4 * fq;
;                         const unsigned ug = *(const unsigned*)(sg + off);
;                         const float q = (PASS == 0 ? tab[(ai * 128 + wr * 64 + m * 16 + fr) * 4 + 3] : 1.0f) * (1.0f / 255.0f);
;                         float m0 = (float)(ug & 255u) * q * acc[ai][bj][m][n][0], m1 = (float)((ug >> 8) & 255u) * q * acc[ai][bj][m][n][1];
;                         float m2 = (float)((ug >> 16) & 255u) * q * acc[ai][bj][m][n][2], m3 = (float)(ug >> 24) * q * acc[ai][bj][m][n][3];
;                         if (PASS == 1) { const u32x2 t = *(const u32x2*)(merged + off); m0 += bflo(t.x); m1 += bfhi(t.x); m2 += bflo(t.y); m3 += bfhi(t.y); }
;                         u32x2 o; o.x = pk2(m0, m1); o.y = pk2(m2, m3);
;                         *(u32x2*)(merged + off) = o;
;                     }
;             }
;     }
.LBB0_1935:
	s_lshl_b32 s2, s2, 8
	s_ashr_i32 s52, s2, 31
	v_mov_b32_e32 v141, s52
	s_lshl_b64 s[52:53], s[12:13], 18
	v_or_b32_e32 v140, s2, v132
	v_lshl_add_u64 v[142:143], s[52:53], 0, v[134:135]
	v_lshl_add_u64 v[142:143], v[142:143], 0, v[140:141]
	v_lshl_add_u64 v[140:141], s[22:23], 0, v[142:143]
	global_load_dword v155, v[140:141], off
	v_lshl_add_u64 v[144:145], v[142:143], 1, s[44:45]
	global_load_dwordx2 v[146:147], v[144:145], off
	v_or_b32_e32 v148, 16, v142
	v_mov_b32_e32 v149, v143
	v_or_b32_e32 v156, 0x90, v142
	v_mov_b32_e32 v157, v143
	v_lshl_add_u64 v[160:161], v[148:149], 1, s[44:45]
	v_lshl_add_u64 v[158:159], s[22:23], 0, v[148:149]
	v_lshl_add_u64 v[148:149], v[156:157], 1, s[44:45]
	global_load_dwordx2 v[162:163], v[160:161], off
	global_load_dwordx2 v[150:151], v[148:149], off
	s_mov_b64 s[62:63], 0x4000
	s_mov_b64 s[64:65], 0x4010
	s_mov_b64 s[52:53], 0x4080
	s_mov_b32 s2, 0x20000
	s_mov_b32 s12, 0x40000
	v_lshl_add_u64 v[170:171], s[22:23], 0, v[142:143]
	global_load_dword v189, v[170:171], off offset:16
	global_load_dword v190, v[170:171], off offset:128
	global_load_dword v191, v[170:171], off offset:144
	v_lshl_add_u64 v[170:171], v[170:171], 0, s[62:63]
	global_load_dword v192, v[170:171], off
	global_load_dword v193, v[170:171], off offset:16
	global_load_dword v194, v[170:171], off offset:128
	global_load_dword v195, v[170:171], off offset:144
	v_lshl_add_u64 v[170:171], v[170:171], 0, s[62:63]
	global_load_dword v196, v[170:171], off
	global_load_dword v197, v[170:171], off offset:16
	global_load_dword v198, v[170:171], off offset:128
	global_load_dword v199, v[170:171], off offset:144
	v_lshl_add_u64 v[170:171], v[170:171], 0, s[62:63]
	global_load_dword v200, v[170:171], off
	global_load_dword v201, v[170:171], off offset:16
	global_load_dword v202, v[170:171], off offset:128
	global_load_dword v203, v[170:171], off offset:144
	v_lshl_add_u64 v[170:171], v[170:171], 0, s[62:63]
	v_lshl_add_u64 v[170:171], v[170:171], 0, s[62:63]
	v_lshl_add_u64 v[170:171], v[170:171], 0, s[62:63]
	v_lshl_add_u64 v[170:171], v[170:171], 0, s[62:63]
	v_lshl_add_u64 v[170:171], v[170:171], 0, s[62:63]
	global_load_dword v204, v[170:171], off
	global_load_dword v205, v[170:171], off offset:16
	global_load_dword v206, v[170:171], off offset:128
	global_load_dword v207, v[170:171], off offset:144
	v_lshl_add_u64 v[170:171], v[170:171], 0, s[62:63]
	global_load_dword v208, v[170:171], off
	global_load_dword v209, v[170:171], off offset:16
	global_load_dword v210, v[170:171], off offset:128
	global_load_dword v211, v[170:171], off offset:144
	v_lshl_add_u64 v[170:171], v[170:171], 0, s[62:63]
	global_load_dword v212, v[170:171], off
	global_load_dword v213, v[170:171], off offset:16
	global_load_dword v214, v[170:171], off offset:128
	global_load_dword v215, v[170:171], off offset:144
	v_lshl_add_u64 v[170:171], v[170:171], 0, s[62:63]
	global_load_dword v216, v[170:171], off
	global_load_dword v217, v[170:171], off offset:16
	global_load_dword v218, v[170:171], off offset:128
	global_load_dword v219, v[170:171], off offset:144
	s_waitcnt vmcnt(0)
	v_cvt_f32_ubyte1_e32 v165, v155
	v_cvt_f32_ubyte0_e32 v164, v155
	v_cvt_f32_ubyte3_e32 v169, v155
	v_cvt_f32_ubyte2_e32 v168, v155
	v_lshlrev_b32_e32 v166, 16, v146
	v_and_b32_e32 v167, 0xffff0000, v146
	v_lshlrev_b32_e32 v146, 16, v147
	v_and_b32_e32 v147, 0xffff0000, v147
	v_pk_mul_f32 v[164:165], v[164:165], s[24:25] op_sel_hi:[1,0]
	v_pk_mul_f32 v[168:169], v[168:169], s[24:25] op_sel_hi:[1,0]
	v_pk_fma_f32 v[124:125], v[124:125], v[164:165], v[166:167]
	v_pk_fma_f32 v[126:127], v[126:127], v[168:169], v[146:147]
	v_cvt_pk_bf16_f32 v124, v124, v125
	v_cvt_pk_bf16_f32 v125, v126, v127
	global_store_dwordx2 v[144:145], v[124:125], off
	v_lshlrev_b32_e32 v146, 16, v162
	v_and_b32_e32 v147, 0xffff0000, v162
	v_lshlrev_b32_e32 v158, 16, v163
	v_and_b32_e32 v159, 0xffff0000, v163
	v_or_b32_e32 v124, 0x80, v142
	v_mov_b32_e32 v125, v143
	v_lshl_add_u64 v[126:127], s[22:23], 0, v[124:125]
	v_lshl_add_u64 v[124:125], v[124:125], 1, s[44:45]
	global_load_dwordx2 v[162:163], v[124:125], off
	s_waitcnt vmcnt(1)
	v_cvt_f32_ubyte1_e32 v165, v189
	v_cvt_f32_ubyte0_e32 v164, v189
	v_cvt_f32_ubyte3_e32 v167, v189
	v_cvt_f32_ubyte2_e32 v166, v189
	v_pk_mul_f32 v[164:165], v[164:165], s[24:25] op_sel_hi:[1,0]
	v_pk_mul_f32 v[166:167], v[166:167], s[24:25] op_sel_hi:[1,0]
	v_pk_fma_f32 v[120:121], v[120:121], v[164:165], v[146:147]
	v_pk_fma_f32 v[122:123], v[122:123], v[166:167], v[158:159]
	v_cvt_pk_bf16_f32 v120, v120, v121
	v_cvt_pk_bf16_f32 v121, v122, v123
	global_store_dwordx2 v[160:161], v[120:121], off
	v_lshl_add_u64 v[120:121], s[22:23], 0, v[156:157]
	s_waitcnt vmcnt(1)
	v_lshlrev_b32_e32 v122, 16, v162
	v_and_b32_e32 v123, 0xffff0000, v162
	v_lshlrev_b32_e32 v126, 16, v163
	v_and_b32_e32 v127, 0xffff0000, v163
	s_waitcnt vmcnt(0)
	v_cvt_f32_ubyte1_e32 v147, v190
	v_cvt_f32_ubyte0_e32 v146, v190
	v_cvt_f32_ubyte3_e32 v157, v190
	v_cvt_f32_ubyte2_e32 v156, v190
	v_pk_mul_f32 v[146:147], v[146:147], s[24:25] op_sel_hi:[1,0]
	v_pk_mul_f32 v[156:157], v[156:157], s[24:25] op_sel_hi:[1,0]
	v_pk_fma_f32 v[116:117], v[116:117], v[146:147], v[122:123]
	v_pk_fma_f32 v[118:119], v[118:119], v[156:157], v[126:127]
	v_cvt_pk_bf16_f32 v116, v116, v117
	v_cvt_pk_bf16_f32 v117, v118, v119
	global_store_dwordx2 v[124:125], v[116:117], off
	v_lshlrev_b32_e32 v120, 16, v150
	v_and_b32_e32 v121, 0xffff0000, v150
	v_lshlrev_b32_e32 v122, 16, v151
	v_and_b32_e32 v123, 0xffff0000, v151
	v_lshl_add_u64 v[116:117], v[142:143], 0, s[62:63]
	v_lshl_add_u64 v[118:119], s[22:23], 0, v[116:117]
	s_mov_b64 s[62:63], 0x4090
	s_waitcnt vmcnt(0)
; DI unsigned pk2(float a, float b) { f32x2 v = {a, b}; return __builtin_bit_cast(unsigned, __builtin_convertvector(v, bfv2)); }
; DI float bflo(unsigned u) { return __uint_as_float(u << 16); }
; DI float bfhi(unsigned u) { return __uint_as_float(u & 0xffff0000u); }
;     DI void operator()(const pg8::f32x4 (&acc)[2][2][4][2], const pg8::Unit& u, int wr, int wc, int fr, int fq) const {
;         const unsigned char* sg = ws + (PASS == 0 ? OFF_SGB : OFF_SGA);
;         bf16_t* merged = (bf16_t*)(ws + OFF_AK);
; #pragma unroll
;         for (int ai = 0; ai < 2; ++ai)
; #pragma unroll
;             for (int m = 0; m < 4; ++m) {
;                 const size_t tok = (size_t)u.pm * 256 + ai * 128 + wr * 64 + m * 16 + fr;
; #pragma unroll
;                 for (int bj = 0; bj < 2; ++bj)
; #pragma unroll
;                     for (int n = 0; n < 2; ++n) {
;                         const size_t off = tok * 1024 + u.pn * 256 + bj * 128 + wc * 32 + n * 16 + 4 * fq;
;                         const unsigned ug = *(const unsigned*)(sg + off);
;                         const float q = (PASS == 0 ? tab[(ai * 128 + wr * 64 + m * 16 + fr) * 4 + 3] : 1.0f) * (1.0f / 255.0f);
;                         float m0 = (float)(ug & 255u) * q * acc[ai][bj][m][n][0], m1 = (float)((ug >> 8) & 255u) * q * acc[ai][bj][m][n][1];
;                         float m2 = (float)((ug >> 16) & 255u) * q * acc[ai][bj][m][n][2], m3 = (float)(ug >> 24) * q * acc[ai][bj][m][n][3];
;                         if (PASS == 1) { const u32x2 t = *(const u32x2*)(merged + off); m0 += bflo(t.x); m1 += bfhi(t.x); m2 += bflo(t.y); m3 += bfhi(t.y); }
;                         u32x2 o; o.x = pk2(m0, m1); o.y = pk2(m2, m3);
;                         *(u32x2*)(merged + off) = o;
;                     }
;             }
;     }
	v_cvt_f32_ubyte1_e32 v125, v191
	v_cvt_f32_ubyte0_e32 v124, v191
	v_cvt_f32_ubyte3_e32 v127, v191
	v_cvt_f32_ubyte2_e32 v126, v191
	v_pk_mul_f32 v[124:125], v[124:125], s[24:25] op_sel_hi:[1,0]
	v_pk_mul_f32 v[126:127], v[126:127], s[24:25] op_sel_hi:[1,0]
	v_pk_fma_f32 v[112:113], v[112:113], v[124:125], v[120:121]
	v_pk_fma_f32 v[114:115], v[114:115], v[126:127], v[122:123]
	v_cvt_pk_bf16_f32 v112, v112, v113
	v_cvt_pk_bf16_f32 v113, v114, v115
	global_store_dwordx2 v[148:149], v[112:113], off
	v_lshl_add_u64 v[112:113], v[116:117], 1, s[44:45]
	global_load_dwordx2 v[114:115], v[112:113], off
	v_lshl_add_u64 v[116:117], v[142:143], 0, s[64:65]
	v_lshl_add_u64 v[120:121], v[142:143], 0, s[62:63]
	v_lshl_add_u64 v[124:125], v[116:117], 1, s[44:45]
	v_lshl_add_u64 v[122:123], s[22:23], 0, v[116:117]
	v_lshl_add_u64 v[116:117], v[120:121], 1, s[44:45]
	global_load_dwordx2 v[126:127], v[124:125], off
	global_load_dwordx2 v[118:119], v[116:117], off
	s_mov_b64 s[62:63], 0x8000
	s_mov_b64 s[64:65], 0x8010
	s_waitcnt vmcnt(3)
	v_cvt_f32_ubyte1_e32 v147, v192
	v_cvt_f32_ubyte0_e32 v146, v192
	v_cvt_f32_ubyte3_e32 v151, v192
	v_cvt_f32_ubyte2_e32 v150, v192
	s_waitcnt vmcnt(2)
	v_lshlrev_b32_e32 v148, 16, v114
	v_and_b32_e32 v149, 0xffff0000, v114
	v_lshlrev_b32_e32 v114, 16, v115
	v_and_b32_e32 v115, 0xffff0000, v115
	v_pk_mul_f32 v[146:147], v[146:147], s[24:25] op_sel_hi:[1,0]
	v_pk_mul_f32 v[150:151], v[150:151], s[24:25] op_sel_hi:[1,0]
	v_pk_fma_f32 v[108:109], v[108:109], v[146:147], v[148:149]
	v_pk_fma_f32 v[110:111], v[110:111], v[150:151], v[114:115]
	v_cvt_pk_bf16_f32 v108, v108, v109
	v_cvt_pk_bf16_f32 v109, v110, v111
	global_store_dwordx2 v[112:113], v[108:109], off
	s_waitcnt vmcnt(2)
	v_lshlrev_b32_e32 v112, 16, v126
	v_and_b32_e32 v113, 0xffff0000, v126
	v_lshlrev_b32_e32 v114, 16, v127
	v_and_b32_e32 v115, 0xffff0000, v127
	v_lshl_add_u64 v[108:109], v[142:143], 0, s[52:53]
	v_lshl_add_u64 v[110:111], s[22:23], 0, v[108:109]
	v_lshl_add_u64 v[108:109], v[108:109], 1, s[44:45]
	global_load_dwordx2 v[122:123], v[108:109], off
	s_mov_b64 s[52:53], 0x8080
	s_waitcnt vmcnt(1)
	v_cvt_f32_ubyte1_e32 v127, v193
	v_cvt_f32_ubyte0_e32 v126, v193
	v_cvt_f32_ubyte3_e32 v147, v193
	v_cvt_f32_ubyte2_e32 v146, v193
	v_pk_mul_f32 v[126:127], v[126:127], s[24:25] op_sel_hi:[1,0]
	v_pk_mul_f32 v[146:147], v[146:147], s[24:25] op_sel_hi:[1,0]
	v_pk_fma_f32 v[104:105], v[104:105], v[126:127], v[112:113]
	v_pk_fma_f32 v[106:107], v[106:107], v[146:147], v[114:115]
	v_cvt_pk_bf16_f32 v104, v104, v105
	v_cvt_pk_bf16_f32 v105, v106, v107
	global_store_dwordx2 v[124:125], v[104:105], off
	s_waitcnt vmcnt(1)
	v_lshlrev_b32_e32 v106, 16, v122
	v_and_b32_e32 v107, 0xffff0000, v122
	v_lshlrev_b32_e32 v110, 16, v123
	v_and_b32_e32 v111, 0xffff0000, v123
	v_lshl_add_u64 v[104:105], s[22:23], 0, v[120:121]
	s_waitcnt vmcnt(0)
	v_cvt_f32_ubyte1_e32 v113, v194
	v_cvt_f32_ubyte0_e32 v112, v194
	v_cvt_f32_ubyte3_e32 v115, v194
	v_cvt_f32_ubyte2_e32 v114, v194
	v_pk_mul_f32 v[112:113], v[112:113], s[24:25] op_sel_hi:[1,0]
	v_pk_mul_f32 v[114:115], v[114:115], s[24:25] op_sel_hi:[1,0]
	v_pk_fma_f32 v[100:101], v[100:101], v[112:113], v[106:107]
	v_pk_fma_f32 v[102:103], v[102:103], v[114:115], v[110:111]
	v_cvt_pk_bf16_f32 v100, v100, v101
	v_cvt_pk_bf16_f32 v101, v102, v103
	global_store_dwordx2 v[108:109], v[100:101], off
	v_lshlrev_b32_e32 v104, 16, v118
	v_and_b32_e32 v105, 0xffff0000, v118
	v_lshlrev_b32_e32 v106, 16, v119
	v_and_b32_e32 v107, 0xffff0000, v119
	v_lshl_add_u64 v[100:101], v[142:143], 0, s[62:63]
	v_lshl_add_u64 v[102:103], s[22:23], 0, v[100:101]
	s_mov_b64 s[62:63], 0x8090
	s_waitcnt vmcnt(0)
	v_cvt_f32_ubyte1_e32 v109, v195
	v_cvt_f32_ubyte0_e32 v108, v195
	v_cvt_f32_ubyte3_e32 v111, v195
	v_cvt_f32_ubyte2_e32 v110, v195
	v_pk_mul_f32 v[108:109], v[108:109], s[24:25] op_sel_hi:[1,0]
	v_pk_mul_f32 v[110:111], v[110:111], s[24:25] op_sel_hi:[1,0]
	v_pk_fma_f32 v[96:97], v[96:97], v[108:109], v[104:105]
	v_pk_fma_f32 v[98:99], v[98:99], v[110:111], v[106:107]
	v_cvt_pk_bf16_f32 v96, v96, v97
	v_cvt_pk_bf16_f32 v97, v98, v99
	global_store_dwordx2 v[116:117], v[96:97], off
	v_lshl_add_u64 v[96:97], v[100:101], 1, s[44:45]
	global_load_dwordx2 v[98:99], v[96:97], off
	v_lshl_add_u64 v[100:101], v[142:143], 0, s[64:65]
	v_lshl_add_u64 v[104:105], v[142:143], 0, s[62:63]
	v_lshl_add_u64 v[108:109], v[100:101], 1, s[44:45]
	v_lshl_add_u64 v[106:107], s[22:23], 0, v[100:101]
	v_lshl_add_u64 v[100:101], v[104:105], 1, s[44:45]
	global_load_dwordx2 v[110:111], v[108:109], off
	global_load_dwordx2 v[102:103], v[100:101], off
	s_mov_b64 s[62:63], 0xc000
	s_mov_b64 s[64:65], 0xc010
	s_waitcnt vmcnt(3)
	v_cvt_f32_ubyte1_e32 v113, v196
	v_cvt_f32_ubyte0_e32 v112, v196
	v_cvt_f32_ubyte3_e32 v117, v196
	v_cvt_f32_ubyte2_e32 v116, v196
	s_waitcnt vmcnt(2)
	v_lshlrev_b32_e32 v114, 16, v98
	v_and_b32_e32 v115, 0xffff0000, v98
	v_lshlrev_b32_e32 v98, 16, v99
	v_and_b32_e32 v99, 0xffff0000, v99
	v_pk_mul_f32 v[112:113], v[112:113], s[24:25] op_sel_hi:[1,0]
	v_pk_mul_f32 v[116:117], v[116:117], s[24:25] op_sel_hi:[1,0]
	v_pk_fma_f32 v[92:93], v[92:93], v[112:113], v[114:115]
	v_pk_fma_f32 v[94:95], v[94:95], v[116:117], v[98:99]
	v_cvt_pk_bf16_f32 v92, v92, v93
	v_cvt_pk_bf16_f32 v93, v94, v95
	global_store_dwordx2 v[96:97], v[92:93], off
	s_waitcnt vmcnt(2)
	v_lshlrev_b32_e32 v96, 16, v110
	v_and_b32_e32 v97, 0xffff0000, v110
	v_lshlrev_b32_e32 v98, 16, v111
	v_and_b32_e32 v99, 0xffff0000, v111
	v_lshl_add_u64 v[92:93], v[142:143], 0, s[52:53]
	v_lshl_add_u64 v[94:95], s[22:23], 0, v[92:93]
	v_lshl_add_u64 v[92:93], v[92:93], 1, s[44:45]
	global_load_dwordx2 v[106:107], v[92:93], off
	s_mov_b64 s[52:53], 0xc080
	s_waitcnt vmcnt(1)
; DI unsigned pk2(float a, float b) { f32x2 v = {a, b}; return __builtin_bit_cast(unsigned, __builtin_convertvector(v, bfv2)); }
; DI float bflo(unsigned u) { return __uint_as_float(u << 16); }
; DI float bfhi(unsigned u) { return __uint_as_float(u & 0xffff0000u); }
;     DI void operator()(const pg8::f32x4 (&acc)[2][2][4][2], const pg8::Unit& u, int wr, int wc, int fr, int fq) const {
;         const unsigned char* sg = ws + (PASS == 0 ? OFF_SGB : OFF_SGA);
;         bf16_t* merged = (bf16_t*)(ws + OFF_AK);
; #pragma unroll
;         for (int ai = 0; ai < 2; ++ai)
; #pragma unroll
;             for (int m = 0; m < 4; ++m) {
;                 const size_t tok = (size_t)u.pm * 256 + ai * 128 + wr * 64 + m * 16 + fr;
; #pragma unroll
;                 for (int bj = 0; bj < 2; ++bj)
; #pragma unroll
;                     for (int n = 0; n < 2; ++n) {
;                         const size_t off = tok * 1024 + u.pn * 256 + bj * 128 + wc * 32 + n * 16 + 4 * fq;
;                         const unsigned ug = *(const unsigned*)(sg + off);
;                         const float q = (PASS == 0 ? tab[(ai * 128 + wr * 64 + m * 16 + fr) * 4 + 3] : 1.0f) * (1.0f / 255.0f);
;                         float m0 = (float)(ug & 255u) * q * acc[ai][bj][m][n][0], m1 = (float)((ug >> 8) & 255u) * q * acc[ai][bj][m][n][1];
;                         float m2 = (float)((ug >> 16) & 255u) * q * acc[ai][bj][m][n][2], m3 = (float)(ug >> 24) * q * acc[ai][bj][m][n][3];
;                         if (PASS == 1) { const u32x2 t = *(const u32x2*)(merged + off); m0 += bflo(t.x); m1 += bfhi(t.x); m2 += bflo(t.y); m3 += bfhi(t.y); }
;                         u32x2 o; o.x = pk2(m0, m1); o.y = pk2(m2, m3);
;                         *(u32x2*)(merged + off) = o;
;                     }
;             }
;     }
	v_cvt_f32_ubyte1_e32 v111, v197
	v_cvt_f32_ubyte0_e32 v110, v197
	v_cvt_f32_ubyte3_e32 v113, v197
	v_cvt_f32_ubyte2_e32 v112, v197
	v_pk_mul_f32 v[110:111], v[110:111], s[24:25] op_sel_hi:[1,0]
	v_pk_mul_f32 v[112:113], v[112:113], s[24:25] op_sel_hi:[1,0]
	v_pk_fma_f32 v[88:89], v[88:89], v[110:111], v[96:97]
	v_pk_fma_f32 v[90:91], v[90:91], v[112:113], v[98:99]
	v_cvt_pk_bf16_f32 v88, v88, v89
	v_cvt_pk_bf16_f32 v89, v90, v91
	global_store_dwordx2 v[108:109], v[88:89], off
	s_waitcnt vmcnt(1)
	v_lshlrev_b32_e32 v90, 16, v106
	v_and_b32_e32 v91, 0xffff0000, v106
	v_lshlrev_b32_e32 v94, 16, v107
	v_and_b32_e32 v95, 0xffff0000, v107
	v_lshl_add_u64 v[88:89], s[22:23], 0, v[104:105]
	s_waitcnt vmcnt(0)
	v_cvt_f32_ubyte1_e32 v97, v198
	v_cvt_f32_ubyte0_e32 v96, v198
	v_cvt_f32_ubyte3_e32 v99, v198
	v_cvt_f32_ubyte2_e32 v98, v198
	v_pk_mul_f32 v[96:97], v[96:97], s[24:25] op_sel_hi:[1,0]
	v_pk_mul_f32 v[98:99], v[98:99], s[24:25] op_sel_hi:[1,0]
	v_pk_fma_f32 v[84:85], v[84:85], v[96:97], v[90:91]
	v_pk_fma_f32 v[86:87], v[86:87], v[98:99], v[94:95]
	v_cvt_pk_bf16_f32 v84, v84, v85
	v_cvt_pk_bf16_f32 v85, v86, v87
	global_store_dwordx2 v[92:93], v[84:85], off
	v_lshlrev_b32_e32 v88, 16, v102
	v_and_b32_e32 v89, 0xffff0000, v102
	v_lshlrev_b32_e32 v90, 16, v103
	v_and_b32_e32 v91, 0xffff0000, v103
	v_lshl_add_u64 v[84:85], v[142:143], 0, s[62:63]
	v_lshl_add_u64 v[86:87], s[22:23], 0, v[84:85]
	s_mov_b64 s[62:63], 0xc090
	s_waitcnt vmcnt(0)
	v_cvt_f32_ubyte1_e32 v93, v199
	v_cvt_f32_ubyte0_e32 v92, v199
	v_cvt_f32_ubyte3_e32 v95, v199
	v_cvt_f32_ubyte2_e32 v94, v199
	v_pk_mul_f32 v[92:93], v[92:93], s[24:25] op_sel_hi:[1,0]
	v_pk_mul_f32 v[94:95], v[94:95], s[24:25] op_sel_hi:[1,0]
	v_pk_fma_f32 v[80:81], v[80:81], v[92:93], v[88:89]
	v_pk_fma_f32 v[82:83], v[82:83], v[94:95], v[90:91]
	v_cvt_pk_bf16_f32 v80, v80, v81
	v_cvt_pk_bf16_f32 v81, v82, v83
	global_store_dwordx2 v[100:101], v[80:81], off
	v_lshl_add_u64 v[80:81], v[84:85], 1, s[44:45]
	global_load_dwordx2 v[82:83], v[80:81], off
	v_lshl_add_u64 v[84:85], v[142:143], 0, s[64:65]
	v_lshl_add_u64 v[88:89], v[142:143], 0, s[62:63]
	v_lshl_add_u64 v[92:93], v[84:85], 1, s[44:45]
	v_lshl_add_u64 v[90:91], s[22:23], 0, v[84:85]
	v_lshl_add_u64 v[84:85], v[88:89], 1, s[44:45]
	global_load_dwordx2 v[94:95], v[92:93], off
	global_load_dwordx2 v[86:87], v[84:85], off
	s_waitcnt vmcnt(3)
	v_cvt_f32_ubyte1_e32 v97, v200
	v_cvt_f32_ubyte0_e32 v96, v200
	v_cvt_f32_ubyte3_e32 v101, v200
	v_cvt_f32_ubyte2_e32 v100, v200
	s_waitcnt vmcnt(2)
	v_lshlrev_b32_e32 v98, 16, v82
	v_and_b32_e32 v99, 0xffff0000, v82
	v_lshlrev_b32_e32 v82, 16, v83
	v_and_b32_e32 v83, 0xffff0000, v83
	v_pk_mul_f32 v[96:97], v[96:97], s[24:25] op_sel_hi:[1,0]
	v_pk_mul_f32 v[100:101], v[100:101], s[24:25] op_sel_hi:[1,0]
	v_pk_fma_f32 v[76:77], v[76:77], v[96:97], v[98:99]
	v_pk_fma_f32 v[78:79], v[78:79], v[100:101], v[82:83]
	v_cvt_pk_bf16_f32 v76, v76, v77
	v_cvt_pk_bf16_f32 v77, v78, v79
	global_store_dwordx2 v[80:81], v[76:77], off
	s_waitcnt vmcnt(2)
	v_lshlrev_b32_e32 v80, 16, v94
	v_and_b32_e32 v81, 0xffff0000, v94
	v_lshlrev_b32_e32 v82, 16, v95
	v_and_b32_e32 v83, 0xffff0000, v95
	v_lshl_add_u64 v[76:77], v[142:143], 0, s[52:53]
	v_lshl_add_u64 v[78:79], s[22:23], 0, v[76:77]
	v_lshl_add_u64 v[76:77], v[76:77], 1, s[44:45]
	global_load_dwordx2 v[90:91], v[76:77], off
	s_waitcnt vmcnt(1)
	v_cvt_f32_ubyte1_e32 v95, v201
	v_cvt_f32_ubyte0_e32 v94, v201
	v_cvt_f32_ubyte3_e32 v97, v201
	v_cvt_f32_ubyte2_e32 v96, v201
	v_pk_mul_f32 v[94:95], v[94:95], s[24:25] op_sel_hi:[1,0]
	v_pk_mul_f32 v[96:97], v[96:97], s[24:25] op_sel_hi:[1,0]
	v_pk_fma_f32 v[72:73], v[72:73], v[94:95], v[80:81]
	v_pk_fma_f32 v[74:75], v[74:75], v[96:97], v[82:83]
	v_cvt_pk_bf16_f32 v72, v72, v73
	v_cvt_pk_bf16_f32 v73, v74, v75
	global_store_dwordx2 v[92:93], v[72:73], off
	s_waitcnt vmcnt(1)
	v_lshlrev_b32_e32 v74, 16, v90
	v_and_b32_e32 v75, 0xffff0000, v90
	v_lshlrev_b32_e32 v78, 16, v91
	v_and_b32_e32 v79, 0xffff0000, v91
	v_lshl_add_u64 v[72:73], s[22:23], 0, v[88:89]
	s_waitcnt vmcnt(0)
	v_cvt_f32_ubyte1_e32 v81, v202
	v_cvt_f32_ubyte0_e32 v80, v202
	v_cvt_f32_ubyte3_e32 v83, v202
	v_cvt_f32_ubyte2_e32 v82, v202
	v_pk_mul_f32 v[80:81], v[80:81], s[24:25] op_sel_hi:[1,0]
	v_pk_mul_f32 v[82:83], v[82:83], s[24:25] op_sel_hi:[1,0]
	v_pk_fma_f32 v[68:69], v[68:69], v[80:81], v[74:75]
	v_pk_fma_f32 v[70:71], v[70:71], v[82:83], v[78:79]
	v_cvt_pk_bf16_f32 v68, v68, v69
	v_cvt_pk_bf16_f32 v69, v70, v71
	global_store_dwordx2 v[76:77], v[68:69], off
	v_lshlrev_b32_e32 v70, 16, v86
	v_and_b32_e32 v71, 0xffff0000, v86
	v_lshlrev_b32_e32 v72, 16, v87
	v_and_b32_e32 v73, 0xffff0000, v87
	v_add_co_u32_e32 v68, vcc, s2, v140
	s_waitcnt vmcnt(0)
	v_cvt_f32_ubyte1_e32 v75, v203
	v_cvt_f32_ubyte0_e32 v74, v203
	v_cvt_f32_ubyte3_e32 v77, v203
	v_cvt_f32_ubyte2_e32 v76, v203
	v_pk_mul_f32 v[74:75], v[74:75], s[24:25] op_sel_hi:[1,0]
	v_pk_mul_f32 v[76:77], v[76:77], s[24:25] op_sel_hi:[1,0]
	v_pk_fma_f32 v[64:65], v[64:65], v[74:75], v[70:71]
	v_pk_fma_f32 v[66:67], v[66:67], v[76:77], v[72:73]
	v_cvt_pk_bf16_f32 v64, v64, v65
	v_cvt_pk_bf16_f32 v65, v66, v67
	v_addc_co_u32_e32 v69, vcc, 0, v141, vcc
	global_store_dwordx2 v[84:85], v[64:65], off
	v_add_co_u32_e32 v68, vcc, s12, v144
	v_lshl_add_u64 v[64:65], v[142:143], 0, s[26:27]
	s_nop 0
	v_addc_co_u32_e32 v69, vcc, 0, v145, vcc
	global_load_dwordx2 v[76:77], v[68:69], off
	v_lshl_add_u64 v[72:73], v[142:143], 0, s[30:31]
	v_lshl_add_u64 v[74:75], v[64:65], 1, s[44:45]
	v_lshl_add_u64 v[78:79], s[22:23], 0, v[64:65]
	v_lshl_add_u64 v[64:65], v[72:73], 1, s[44:45]
	global_load_dwordx2 v[70:71], v[74:75], off
	global_load_dwordx2 v[66:67], v[64:65], off
	v_lshl_add_u64 v[72:73], s[22:23], 0, v[72:73]
	s_waitcnt vmcnt(3)
; DI unsigned pk2(float a, float b) { f32x2 v = {a, b}; return __builtin_bit_cast(unsigned, __builtin_convertvector(v, bfv2)); }
; DI float bflo(unsigned u) { return __uint_as_float(u << 16); }
; DI float bfhi(unsigned u) { return __uint_as_float(u & 0xffff0000u); }
;     DI void operator()(const pg8::f32x4 (&acc)[2][2][4][2], const pg8::Unit& u, int wr, int wc, int fr, int fq) const {
;     ...
;                 const size_t tok = (size_t)u.pm * 256 + ai * 128 + wr * 64 + m * 16 + fr;
; #pragma unroll
;                 for (int bj = 0; bj < 2; ++bj)
; #pragma unroll
;                     for (int n = 0; n < 2; ++n) {
;                         const size_t off = tok * 1024 + u.pn * 256 + bj * 128 + wc * 32 + n * 16 + 4 * fq;
;                         const unsigned ug = *(const unsigned*)(sg + off);
;                         const float q = (PASS == 0 ? tab[(ai * 128 + wr * 64 + m * 16 + fr) * 4 + 3] : 1.0f) * (1.0f / 255.0f);
;                         float m0 = (float)(ug & 255u) * q * acc[ai][bj][m][n][0], m1 = (float)((ug >> 8) & 255u) * q * acc[ai][bj][m][n][1];
;                         float m2 = (float)((ug >> 16) & 255u) * q * acc[ai][bj][m][n][2], m3 = (float)(ug >> 24) * q * acc[ai][bj][m][n][3];
;                         if (PASS == 1) { const u32x2 t = *(const u32x2*)(merged + off); m0 += bflo(t.x); m1 += bfhi(t.x); m2 += bflo(t.y); m3 += bfhi(t.y); }
;                         u32x2 o; o.x = pk2(m0, m1); o.y = pk2(m2, m3);
;                         *(u32x2*)(merged + off) = o;
	v_cvt_f32_ubyte1_e32 v81, v204
	v_cvt_f32_ubyte0_e32 v80, v204
	v_cvt_f32_ubyte3_e32 v85, v204
	v_cvt_f32_ubyte2_e32 v84, v204
	v_pk_mul_f32 v[80:81], v[80:81], s[24:25] op_sel_hi:[1,0]
	v_pk_mul_f32 v[84:85], v[84:85], s[24:25] op_sel_hi:[1,0]
	s_waitcnt vmcnt(2)
	v_lshlrev_b32_e32 v82, 16, v76
	v_and_b32_e32 v83, 0xffff0000, v76
	v_lshlrev_b32_e32 v76, 16, v77
	v_and_b32_e32 v77, 0xffff0000, v77
	v_pk_fma_f32 v[60:61], v[60:61], v[80:81], v[82:83]
	v_pk_fma_f32 v[62:63], v[62:63], v[84:85], v[76:77]
	v_cvt_pk_bf16_f32 v60, v60, v61
	v_cvt_pk_bf16_f32 v61, v62, v63
	global_store_dwordx2 v[68:69], v[60:61], off
	s_waitcnt vmcnt(2)
	v_lshlrev_b32_e32 v86, 16, v70
	v_and_b32_e32 v87, 0xffff0000, v70
	v_lshlrev_b32_e32 v88, 16, v71
	v_and_b32_e32 v89, 0xffff0000, v71
	v_lshl_add_u64 v[62:63], v[142:143], 0, s[28:29]
	v_lshl_add_u64 v[60:61], v[142:143], 0, s[34:35]
	v_lshl_add_u64 v[68:69], v[142:143], 0, s[42:43]
	v_lshl_add_u64 v[84:85], v[62:63], 1, s[44:45]
	v_lshl_add_u64 v[82:83], s[22:23], 0, v[62:63]
	v_lshl_add_u64 v[76:77], v[60:61], 1, s[44:45]
	v_lshl_add_u64 v[62:63], v[68:69], 1, s[44:45]
	global_load_dwordx2 v[90:91], v[84:85], off
	global_load_dwordx2 v[78:79], v[76:77], off
	global_load_dwordx2 v[70:71], v[62:63], off
	s_waitcnt vmcnt(3)
	v_cvt_f32_ubyte1_e32 v93, v205
	v_cvt_f32_ubyte0_e32 v92, v205
	v_cvt_f32_ubyte3_e32 v81, v205
	v_cvt_f32_ubyte2_e32 v80, v205
	v_pk_mul_f32 v[92:93], v[92:93], s[24:25] op_sel_hi:[1,0]
	v_pk_mul_f32 v[80:81], v[80:81], s[24:25] op_sel_hi:[1,0]
	v_pk_fma_f32 v[56:57], v[56:57], v[92:93], v[86:87]
	v_pk_fma_f32 v[58:59], v[58:59], v[80:81], v[88:89]
	v_cvt_pk_bf16_f32 v56, v56, v57
	v_cvt_pk_bf16_f32 v57, v58, v59
	global_store_dwordx2 v[74:75], v[56:57], off
	s_waitcnt vmcnt(3)
	v_lshlrev_b32_e32 v80, 16, v90
	v_and_b32_e32 v81, 0xffff0000, v90
	v_lshlrev_b32_e32 v86, 16, v91
	v_and_b32_e32 v87, 0xffff0000, v91
	v_add_co_u32_e32 v74, vcc, s79, v144
	s_waitcnt vmcnt(0)
	v_cvt_f32_ubyte1_e32 v89, v206
	v_cvt_f32_ubyte0_e32 v88, v206
	v_cvt_f32_ubyte3_e32 v91, v206
	v_cvt_f32_ubyte2_e32 v90, v206
	v_pk_mul_f32 v[88:89], v[88:89], s[24:25] op_sel_hi:[1,0]
	v_pk_mul_f32 v[90:91], v[90:91], s[24:25] op_sel_hi:[1,0]
	v_addc_co_u32_e32 v75, vcc, 0, v145, vcc
	v_pk_fma_f32 v[52:53], v[52:53], v[88:89], v[80:81]
	v_pk_fma_f32 v[54:55], v[54:55], v[90:91], v[86:87]
	v_add_co_u32_e32 v56, vcc, s81, v144
	v_cvt_pk_bf16_f32 v52, v52, v53
	v_cvt_pk_bf16_f32 v53, v54, v55
	v_addc_co_u32_e32 v57, vcc, 0, v145, vcc
	global_load_dwordx2 v[82:83], v[74:75], off
	global_load_dwordx2 v[58:59], v[56:57], off
	v_lshlrev_b32_e32 v88, 16, v66
	global_store_dwordx2 v[84:85], v[52:53], off
	v_add_co_u32_e32 v84, vcc, s78, v140
	v_and_b32_e32 v89, 0xffff0000, v66
	v_lshlrev_b32_e32 v66, 16, v67
	v_and_b32_e32 v67, 0xffff0000, v67
	v_lshl_add_u64 v[80:81], v[142:143], 0, s[36:37]
	v_addc_co_u32_e32 v85, vcc, 0, v141, vcc
	v_lshl_add_u64 v[72:73], v[80:81], 1, s[44:45]
	v_add_co_u32_e32 v52, vcc, s83, v144
	s_waitcnt vmcnt(0)
	v_cvt_f32_ubyte1_e32 v91, v207
	v_cvt_f32_ubyte0_e32 v90, v207
	v_cvt_f32_ubyte3_e32 v93, v207
	v_cvt_f32_ubyte2_e32 v92, v207
	v_pk_mul_f32 v[90:91], v[90:91], s[24:25] op_sel_hi:[1,0]
	v_pk_mul_f32 v[92:93], v[92:93], s[24:25] op_sel_hi:[1,0]
	v_pk_fma_f32 v[48:49], v[48:49], v[90:91], v[88:89]
	v_pk_fma_f32 v[50:51], v[50:51], v[92:93], v[66:67]
	v_cvt_pk_bf16_f32 v48, v48, v49
	v_cvt_pk_bf16_f32 v49, v50, v51
	v_addc_co_u32_e32 v53, vcc, 0, v145, vcc
	global_load_dwordx2 v[86:87], v[72:73], off
	global_load_dwordx2 v[54:55], v[52:53], off
	v_lshlrev_b32_e32 v66, 16, v82
	global_store_dwordx2 v[64:65], v[48:49], off
	v_and_b32_e32 v67, 0xffff0000, v82
	v_lshlrev_b32_e32 v82, 16, v83
	v_and_b32_e32 v83, 0xffff0000, v83
	v_lshl_add_u64 v[84:85], v[142:143], 0, s[38:39]
	v_lshl_add_u64 v[50:51], v[142:143], 0, s[56:57]
	v_lshl_add_u64 v[88:89], v[84:85], 1, s[44:45]
	v_lshl_add_u64 v[64:65], s[22:23], 0, v[60:61]
	v_lshl_add_u64 v[48:49], v[50:51], 1, s[44:45]
	global_load_dwordx2 v[90:91], v[88:89], off
	global_load_dwordx2 v[60:61], v[48:49], off
	s_waitcnt vmcnt(2)
	v_cvt_f32_ubyte1_e32 v93, v208
	v_cvt_f32_ubyte0_e32 v92, v208
	v_cvt_f32_ubyte3_e32 v95, v208
	v_cvt_f32_ubyte2_e32 v94, v208
	v_pk_mul_f32 v[92:93], v[92:93], s[24:25] op_sel_hi:[1,0]
	v_pk_mul_f32 v[94:95], v[94:95], s[24:25] op_sel_hi:[1,0]
	v_pk_fma_f32 v[44:45], v[44:45], v[92:93], v[66:67]
	v_pk_fma_f32 v[46:47], v[46:47], v[94:95], v[82:83]
	v_cvt_pk_bf16_f32 v44, v44, v45
	v_cvt_pk_bf16_f32 v45, v46, v47
	global_store_dwordx2 v[74:75], v[44:45], off
	v_lshl_add_u64 v[46:47], s[22:23], 0, v[80:81]
	v_lshlrev_b32_e32 v66, 16, v78
	v_and_b32_e32 v67, 0xffff0000, v78
	v_lshlrev_b32_e32 v78, 16, v79
	v_and_b32_e32 v79, 0xffff0000, v79
	v_lshl_add_u64 v[74:75], v[142:143], 0, s[40:41]
	v_lshl_add_u64 v[44:45], v[74:75], 1, s[44:45]
	global_load_dwordx2 v[64:65], v[44:45], off
	v_lshl_add_u64 v[74:75], s[22:23], 0, v[74:75]
	s_waitcnt vmcnt(1)
	v_cvt_f32_ubyte1_e32 v81, v209
	v_cvt_f32_ubyte0_e32 v80, v209
	v_cvt_f32_ubyte3_e32 v83, v209
	v_cvt_f32_ubyte2_e32 v82, v209
	v_pk_mul_f32 v[80:81], v[80:81], s[24:25] op_sel_hi:[1,0]
	v_pk_mul_f32 v[82:83], v[82:83], s[24:25] op_sel_hi:[1,0]
	v_pk_fma_f32 v[40:41], v[40:41], v[80:81], v[66:67]
	v_pk_fma_f32 v[42:43], v[42:43], v[82:83], v[78:79]
	v_cvt_pk_bf16_f32 v40, v40, v41
	v_cvt_pk_bf16_f32 v41, v42, v43
	global_store_dwordx2 v[76:77], v[40:41], off
	v_lshl_add_u64 v[66:67], v[142:143], 0, s[48:49]
	v_lshl_add_u64 v[40:41], v[66:67], 1, s[44:45]
	global_load_dwordx2 v[42:43], v[40:41], off
	v_lshlrev_b32_e32 v76, 16, v86
	v_and_b32_e32 v77, 0xffff0000, v86
	v_lshlrev_b32_e32 v78, 16, v87
	v_and_b32_e32 v79, 0xffff0000, v87
	v_lshl_add_u64 v[46:47], s[22:23], 0, v[84:85]
	s_waitcnt vmcnt(1)
; DI unsigned pk2(float a, float b) { f32x2 v = {a, b}; return __builtin_bit_cast(unsigned, __builtin_convertvector(v, bfv2)); }
; DI float bflo(unsigned u) { return __uint_as_float(u << 16); }
; DI float bfhi(unsigned u) { return __uint_as_float(u & 0xffff0000u); }
;     DI void operator()(const pg8::f32x4 (&acc)[2][2][4][2], const pg8::Unit& u, int wr, int wc, int fr, int fq) const {
;     ...
;                 const size_t tok = (size_t)u.pm * 256 + ai * 128 + wr * 64 + m * 16 + fr;
; #pragma unroll
;                 for (int bj = 0; bj < 2; ++bj)
; #pragma unroll
;                     for (int n = 0; n < 2; ++n) {
;                         const size_t off = tok * 1024 + u.pn * 256 + bj * 128 + wc * 32 + n * 16 + 4 * fq;
;                         const unsigned ug = *(const unsigned*)(sg + off);
;                         const float q = (PASS == 0 ? tab[(ai * 128 + wr * 64 + m * 16 + fr) * 4 + 3] : 1.0f) * (1.0f / 255.0f);
;                         float m0 = (float)(ug & 255u) * q * acc[ai][bj][m][n][0], m1 = (float)((ug >> 8) & 255u) * q * acc[ai][bj][m][n][1];
;                         float m2 = (float)((ug >> 16) & 255u) * q * acc[ai][bj][m][n][2], m3 = (float)(ug >> 24) * q * acc[ai][bj][m][n][3];
;                         if (PASS == 1) { const u32x2 t = *(const u32x2*)(merged + off); m0 += bflo(t.x); m1 += bfhi(t.x); m2 += bflo(t.y); m3 += bfhi(t.y); }
;                         u32x2 o; o.x = pk2(m0, m1); o.y = pk2(m2, m3);
;                         *(u32x2*)(merged + off) = o;
	v_cvt_f32_ubyte1_e32 v81, v210
	v_cvt_f32_ubyte0_e32 v80, v210
	v_cvt_f32_ubyte3_e32 v83, v210
	v_cvt_f32_ubyte2_e32 v82, v210
	v_pk_mul_f32 v[80:81], v[80:81], s[24:25] op_sel_hi:[1,0]
	v_pk_mul_f32 v[82:83], v[82:83], s[24:25] op_sel_hi:[1,0]
	v_pk_fma_f32 v[36:37], v[36:37], v[80:81], v[76:77]
	v_pk_fma_f32 v[38:39], v[38:39], v[82:83], v[78:79]
	v_cvt_pk_bf16_f32 v36, v36, v37
	v_cvt_pk_bf16_f32 v37, v38, v39
	global_store_dwordx2 v[72:73], v[36:37], off
	v_lshlrev_b32_e32 v76, 16, v90
	v_and_b32_e32 v77, 0xffff0000, v90
	v_lshlrev_b32_e32 v78, 16, v91
	v_and_b32_e32 v79, 0xffff0000, v91
	v_lshl_add_u64 v[46:47], v[142:143], 0, s[54:55]
	v_add_co_u32_e32 v72, vcc, s80, v140
	v_lshl_add_u64 v[36:37], v[46:47], 1, s[44:45]
	s_nop 0
	v_addc_co_u32_e32 v73, vcc, 0, v141, vcc
	global_load_dwordx2 v[38:39], v[36:37], off
	s_waitcnt vmcnt(1)
	v_cvt_f32_ubyte1_e32 v81, v211
	v_cvt_f32_ubyte0_e32 v80, v211
	v_cvt_f32_ubyte3_e32 v83, v211
	v_cvt_f32_ubyte2_e32 v82, v211
	v_pk_mul_f32 v[80:81], v[80:81], s[24:25] op_sel_hi:[1,0]
	v_pk_mul_f32 v[82:83], v[82:83], s[24:25] op_sel_hi:[1,0]
	v_pk_fma_f32 v[32:33], v[32:33], v[80:81], v[76:77]
	v_pk_fma_f32 v[34:35], v[34:35], v[82:83], v[78:79]
	v_cvt_pk_bf16_f32 v32, v32, v33
	v_cvt_pk_bf16_f32 v33, v34, v35
	global_store_dwordx2 v[88:89], v[32:33], off
	v_lshlrev_b32_e32 v76, 16, v58
	v_and_b32_e32 v77, 0xffff0000, v58
	v_lshlrev_b32_e32 v58, 16, v59
	v_and_b32_e32 v59, 0xffff0000, v59
	v_lshl_add_u64 v[72:73], v[142:143], 0, s[58:59]
	v_lshl_add_u64 v[32:33], v[72:73], 1, s[44:45]
	global_load_dwordx2 v[34:35], v[32:33], off
	s_waitcnt vmcnt(1)
	v_cvt_f32_ubyte1_e32 v79, v212
	v_cvt_f32_ubyte0_e32 v78, v212
	v_cvt_f32_ubyte3_e32 v81, v212
	v_cvt_f32_ubyte2_e32 v80, v212
	v_pk_mul_f32 v[78:79], v[78:79], s[24:25] op_sel_hi:[1,0]
	v_pk_mul_f32 v[80:81], v[80:81], s[24:25] op_sel_hi:[1,0]
	v_pk_fma_f32 v[28:29], v[28:29], v[78:79], v[76:77]
	v_pk_fma_f32 v[30:31], v[30:31], v[80:81], v[58:59]
	v_cvt_pk_bf16_f32 v28, v28, v29
	v_cvt_pk_bf16_f32 v29, v30, v31
	global_store_dwordx2 v[56:57], v[28:29], off
	v_lshlrev_b32_e32 v30, 16, v64
	v_and_b32_e32 v31, 0xffff0000, v64
	v_lshlrev_b32_e32 v56, 16, v65
	v_and_b32_e32 v57, 0xffff0000, v65
	v_lshl_add_u64 v[28:29], s[22:23], 0, v[68:69]
	s_waitcnt vmcnt(0)
	v_cvt_f32_ubyte1_e32 v59, v213
	v_cvt_f32_ubyte0_e32 v58, v213
	v_cvt_f32_ubyte3_e32 v65, v213
	v_cvt_f32_ubyte2_e32 v64, v213
	v_pk_mul_f32 v[58:59], v[58:59], s[24:25] op_sel_hi:[1,0]
	v_pk_mul_f32 v[64:65], v[64:65], s[24:25] op_sel_hi:[1,0]
	v_pk_fma_f32 v[24:25], v[24:25], v[58:59], v[30:31]
	v_pk_fma_f32 v[26:27], v[26:27], v[64:65], v[56:57]
	v_cvt_pk_bf16_f32 v24, v24, v25
	v_cvt_pk_bf16_f32 v25, v26, v27
	global_store_dwordx2 v[44:45], v[24:25], off
	v_lshlrev_b32_e32 v26, 16, v70
	v_and_b32_e32 v27, 0xffff0000, v70
	v_lshlrev_b32_e32 v28, 16, v71
	v_and_b32_e32 v29, 0xffff0000, v71
	v_lshl_add_u64 v[24:25], s[22:23], 0, v[66:67]
	s_waitcnt vmcnt(0)
	v_cvt_f32_ubyte1_e32 v31, v214
	v_cvt_f32_ubyte0_e32 v30, v214
	v_cvt_f32_ubyte3_e32 v45, v214
	v_cvt_f32_ubyte2_e32 v44, v214
	v_pk_mul_f32 v[30:31], v[30:31], s[24:25] op_sel_hi:[1,0]
	v_pk_mul_f32 v[44:45], v[44:45], s[24:25] op_sel_hi:[1,0]
	v_pk_fma_f32 v[20:21], v[20:21], v[30:31], v[26:27]
	v_pk_fma_f32 v[22:23], v[22:23], v[44:45], v[28:29]
	v_cvt_pk_bf16_f32 v20, v20, v21
	v_cvt_pk_bf16_f32 v21, v22, v23
	global_store_dwordx2 v[62:63], v[20:21], off
	v_lshlrev_b32_e32 v22, 16, v42
	v_and_b32_e32 v23, 0xffff0000, v42
	v_lshlrev_b32_e32 v24, 16, v43
	v_and_b32_e32 v25, 0xffff0000, v43
	v_add_co_u32_e32 v20, vcc, s82, v140
	s_waitcnt vmcnt(0)
	v_cvt_f32_ubyte1_e32 v27, v215
	v_cvt_f32_ubyte0_e32 v26, v215
	v_cvt_f32_ubyte3_e32 v29, v215
	v_cvt_f32_ubyte2_e32 v28, v215
	v_pk_mul_f32 v[26:27], v[26:27], s[24:25] op_sel_hi:[1,0]
	v_pk_mul_f32 v[28:29], v[28:29], s[24:25] op_sel_hi:[1,0]
	v_pk_fma_f32 v[12:13], v[12:13], v[26:27], v[22:23]
	v_pk_fma_f32 v[14:15], v[14:15], v[28:29], v[24:25]
	v_cvt_pk_bf16_f32 v12, v12, v13
	v_cvt_pk_bf16_f32 v13, v14, v15
	v_addc_co_u32_e32 v21, vcc, 0, v141, vcc
	global_store_dwordx2 v[40:41], v[12:13], off
	v_lshlrev_b32_e32 v14, 16, v54
	v_and_b32_e32 v15, 0xffff0000, v54
	v_lshlrev_b32_e32 v20, 16, v55
	v_and_b32_e32 v21, 0xffff0000, v55
	v_lshl_add_u64 v[12:13], s[22:23], 0, v[46:47]
	s_andn2_b64 vcc, exec, s[60:61]
	s_mov_b64 s[60:61], -1
	s_waitcnt vmcnt(0)
	v_cvt_f32_ubyte1_e32 v23, v216
	v_cvt_f32_ubyte0_e32 v22, v216
	v_cvt_f32_ubyte3_e32 v25, v216
	v_cvt_f32_ubyte2_e32 v24, v216
	v_pk_mul_f32 v[22:23], v[22:23], s[24:25] op_sel_hi:[1,0]
	v_pk_mul_f32 v[24:25], v[24:25], s[24:25] op_sel_hi:[1,0]
	v_pk_fma_f32 v[14:15], v[16:17], v[22:23], v[14:15]
	v_pk_fma_f32 v[16:17], v[18:19], v[24:25], v[20:21]
	v_cvt_pk_bf16_f32 v14, v14, v15
	v_cvt_pk_bf16_f32 v15, v16, v17
	global_store_dwordx2 v[52:53], v[14:15], off
	v_lshlrev_b32_e32 v14, 16, v38
	v_and_b32_e32 v15, 0xffff0000, v38
	v_lshlrev_b32_e32 v16, 16, v39
	v_and_b32_e32 v17, 0xffff0000, v39
	v_lshl_add_u64 v[12:13], s[22:23], 0, v[50:51]
	s_waitcnt vmcnt(0)
	v_cvt_f32_ubyte1_e32 v19, v217
	v_cvt_f32_ubyte0_e32 v18, v217
	v_cvt_f32_ubyte3_e32 v21, v217
	v_cvt_f32_ubyte2_e32 v20, v217
	v_pk_mul_f32 v[18:19], v[18:19], s[24:25] op_sel_hi:[1,0]
	v_pk_mul_f32 v[20:21], v[20:21], s[24:25] op_sel_hi:[1,0]
	v_pk_fma_f32 v[8:9], v[8:9], v[18:19], v[14:15]
	v_pk_fma_f32 v[10:11], v[10:11], v[20:21], v[16:17]
	v_cvt_pk_bf16_f32 v8, v8, v9
	v_cvt_pk_bf16_f32 v9, v10, v11
	global_store_dwordx2 v[36:37], v[8:9], off
	v_lshlrev_b32_e32 v10, 16, v60
	v_and_b32_e32 v11, 0xffff0000, v60
	v_lshlrev_b32_e32 v12, 16, v61
	v_and_b32_e32 v13, 0xffff0000, v61
	v_lshl_add_u64 v[8:9], s[22:23], 0, v[72:73]
	s_waitcnt vmcnt(0)
	v_cvt_f32_ubyte1_e32 v15, v218
	v_cvt_f32_ubyte0_e32 v14, v218
	v_cvt_f32_ubyte3_e32 v17, v218
	v_cvt_f32_ubyte2_e32 v16, v218
	v_pk_mul_f32 v[14:15], v[14:15], s[24:25] op_sel_hi:[1,0]
	v_pk_mul_f32 v[16:17], v[16:17], s[24:25] op_sel_hi:[1,0]
	v_pk_fma_f32 v[4:5], v[4:5], v[14:15], v[10:11]
	v_pk_fma_f32 v[6:7], v[6:7], v[16:17], v[12:13]
	v_cvt_pk_bf16_f32 v4, v4, v5
	v_cvt_pk_bf16_f32 v5, v6, v7
	global_store_dwordx2 v[48:49], v[4:5], off
	v_lshlrev_b32_e32 v4, 16, v34
	v_and_b32_e32 v5, 0xffff0000, v34
	v_lshlrev_b32_e32 v6, 16, v35
	v_and_b32_e32 v7, 0xffff0000, v35
	s_waitcnt vmcnt(0)
	v_cvt_f32_ubyte1_e32 v9, v219
	v_cvt_f32_ubyte0_e32 v8, v219
	v_cvt_f32_ubyte3_e32 v11, v219
	v_cvt_f32_ubyte2_e32 v10, v219
	v_pk_mul_f32 v[8:9], v[8:9], s[24:25] op_sel_hi:[1,0]
	v_pk_mul_f32 v[10:11], v[10:11], s[24:25] op_sel_hi:[1,0]
	v_pk_fma_f32 v[0:1], v[0:1], v[8:9], v[4:5]
	v_pk_fma_f32 v[2:3], v[2:3], v[10:11], v[6:7]
	v_cvt_pk_bf16_f32 v0, v0, v1
	v_cvt_pk_bf16_f32 v1, v2, v3
	global_store_dwordx2 v[32:33], v[0:1], off
	s_cbranch_vccnz .LBB0_1930
	s_andn2_b64 vcc, exec, s[16:17]
	s_cbranch_vccnz .LBB0_1929
	s_barrier
	s_branch .LBB0_1929
